# v38: v33 + phase-4 second item pass assigned in reversed workgroup order with boundary 0x980 so the double-kmax workgroups skip it
# baseline (speedup 1.0000x reference)
.LBB0_490:
	s_or_b64 exec, exec, s[0:1]
	s_cmp_lg_u32 s32, 0
	s_cbranch_scc1 .Lmy_p4b_done
	s_movk_i32 s32, 0xb78
	s_sub_i32 s29, 0, s29
	s_movk_i32 s96, 0x980
	s_mov_b32 s48, 0x3f800
	s_sub_u32 s22, s24, 0xb00000
	s_subb_u32 s23, s25, 0
	s_sub_u32 s20, s20, 0x1000
	s_subb_u32 s21, s21, 0
	s_branch .LBB0_485

.LBB0_514:
	v_mov_b32_e32 v0, v224
	s_lshl_b32 s0, s97, 3
	s_waitcnt vmcnt(0)
	s_barrier
	s_addk_i32 s0, 0x980
	v_ashrrev_i32_e32 v1, 6, v0
	v_add_u32_e32 v49, s0, v1
	s_movk_i32 s0, 0x1280
	v_cmp_gt_i32_e32 vcc, s0, v49
	s_waitcnt vmcnt(0)
	s_barrier
	s_and_saveexec_b64 s[0:1], vcc
	s_cbranch_execz .LBB0_533
	s_movk_i32 s2, 0x2100
	v_mul_lo_u32 v1, v1, s2
	v_and_b32_e32 v2, 7, v0
	v_readlane_b32 s52, v245, 33
	v_add_u32_e32 v1, 0, v1
	v_bfe_u32 v51, v0, 3, 3
	v_lshlrev_b32_e32 v32, 4, v2
	v_readlane_b32 s60, v245, 41
	v_readlane_b32 s61, v245, 42
	v_add_u32_e32 v0, v1, v32
	v_mul_u32_u24_e32 v3, 0x84, v51
	v_mul_u32_u24_e32 v2, 0x420, v2
	v_lshlrev_b32_e32 v4, 2, v51
	v_mov_b32_e32 v33, 0
	v_readlane_b32 s62, v245, 43
	v_readlane_b32 s63, v245, 44
	v_readlane_b32 s66, v245, 47
	v_readlane_b32 s67, v245, 48
	s_mov_b64 s[12:13], s[60:61]
	v_add3_u32 v61, v1, v2, v4
	v_lshl_add_u64 v[34:35], s[18:19], 0, v[32:33]
	s_mov_b64 s[14:15], s[62:63]
	s_mov_b64 s[18:19], s[66:67]
	s_cmp_lg_u64 s[20:21], 0
	v_mov_b32_e32 v1, 0x7fffea00
	v_add_u32_e32 v63, v0, v3
	v_or_b32_e32 v58, 8, v51
	v_or_b32_e32 v59, 16, v51
	v_or_b32_e32 v60, 24, v51
	v_lshl_add_u64 v[36:37], s[18:19], 0, v[32:33]
	v_lshl_add_u64 v[38:39], s[26:27], 0, v[32:33]
	v_lshl_add_u64 v[40:41], s[14:15], 0, v[32:33]
	v_lshl_add_u64 v[42:43], s[24:25], 0, v[32:33]
	v_lshl_add_u64 v[44:45], s[12:13], 0, v[32:33]
	v_lshl_add_u64 v[46:47], s[22:23], 0, v[32:33]
	s_mov_b64 s[2:3], 0
	s_cselect_b64 s[4:5], -1, 0
	v_lshlrev_b32_e32 v48, 5, v49
	v_lshlrev_b32_e32 v50, 6, v49
	v_lshl_add_u32 v62, v49, 1, v1
	s_movk_i32 s12, 0x57f
	s_movk_i32 s13, 0xaff
	s_movk_i32 s14, 0x107f
	s_movk_i32 s15, 0xf500
	v_add_u32_e32 v64, 0x420, v63
	v_add_u32_e32 v65, 0x428, v63
	v_add_u32_e32 v66, 0x840, v63
	v_add_u32_e32 v67, 0x848, v63
	v_add_u32_e32 v68, 0xc60, v63
	v_add_u32_e32 v69, 0xc68, v63
	v_add_u32_e32 v70, 0x1080, v63
	v_add_u32_e32 v71, 0x1088, v63
	v_add_u32_e32 v72, 0x14a0, v63
	v_add_u32_e32 v73, 0x14a8, v63
	v_add_u32_e32 v74, 0x18c0, v63
	v_add_u32_e32 v75, 0x18c8, v63
	v_add_u32_e32 v76, 0x1ce0, v63
	v_add_u32_e32 v77, 0x1ce8, v63
	s_mov_b32 s18, 0xffc0
	s_movk_i32 s19, 0x2c00
	s_movk_i32 s22, 0x1f00
	s_mov_b32 s23, 0x40000
	s_mov_b32 s24, 0x2e8ba2e9
	s_movk_i32 s25, 0xea00
	s_movk_i32 s26, 0xff00
	v_mov_b32_e32 v78, 1
	v_readlane_b32 s53, v245, 34
	v_readlane_b32 s54, v245, 35
	v_readlane_b32 s55, v245, 36
	v_readlane_b32 s56, v245, 37
	v_readlane_b32 s57, v245, 38
	v_readlane_b32 s58, v245, 39
	v_readlane_b32 s59, v245, 40
	v_readlane_b32 s64, v245, 45
	v_readlane_b32 s65, v245, 46
	s_branch .LBB0_518
